# stack: prep cross-section prefetch + rewritten residual epilogues + per-phase vmcnt(10) waits on top of v47
# speedup vs baseline: 1.0076x; 1.0076x over previous
.LBB0_133:
	s_add_u32 s28, s22, 0x100
	s_addc_u32 s29, s23, 0
	s_add_i32 s85, 0, 0x10000
	v_add_u32_e32 v148, s85, v157
	ds_read_b128 v[130:133], v148
	ds_read_b128 v[134:137], v148 offset:1024
	ds_read_b128 v[138:141], v148 offset:2048
	ds_read_b128 v[148:151], v148 offset:3072
	s_cmp_eq_u32 s84, 40
	s_cselect_b32 s43, s17, s29
	s_cselect_b32 s42, s16, s28
	s_cselect_b32 s41, s19, s79
	s_cselect_b32 s40, s18, s34
	v_lshl_add_u64 v[188:189], s[22:23], 0, v[146:147]
	s_add_i32 m0, s54, 0xc000
	ds_read_b128 v[152:155], v159
	ds_read_b128 v[160:163], v159 offset:1024
	ds_read_b128 v[164:167], v159 offset:2048
	ds_read_b128 v[168:171], v159 offset:3072
	ds_read_b128 v[172:175], v159 offset:4096
	ds_read_b128 v[176:179], v159 offset:5120
	ds_read_b128 v[180:183], v159 offset:6144
	ds_read_b128 v[184:187], v159 offset:7168
	global_load_lds_dwordx4 v[188:189], off
	v_lshl_add_u64 v[188:189], s[22:23], 0, v[144:145]
	s_add_i32 m0, s54, 0xe000
	s_nop 0
	global_load_lds_dwordx4 v[188:189], off
	s_waitcnt lgkmcnt(8)
	s_waitcnt vmcnt(10)
	s_barrier
	s_waitcnt lgkmcnt(0)
	s_waitcnt lgkmcnt(0)
	v_mfma_f32_16x16x32_bf16 v[126:129], v[130:133], v[152:155], v[126:129]
	v_mfma_f32_16x16x32_bf16 v[122:125], v[138:141], v[152:155], v[122:125]
	v_mfma_f32_16x16x32_bf16 v[118:121], v[130:133], v[164:167], v[118:121]
	v_mfma_f32_16x16x32_bf16 v[106:109], v[138:141], v[164:167], v[106:109]
	v_mfma_f32_16x16x32_bf16 v[102:105], v[130:133], v[172:175], v[102:105]
	v_mfma_f32_16x16x32_bf16 v[90:93], v[138:141], v[172:175], v[90:93]
	v_mfma_f32_16x16x32_bf16 v[86:89], v[130:133], v[180:183], v[86:89]
	v_mfma_f32_16x16x32_bf16 v[74:77], v[138:141], v[180:183], v[74:77]
	v_mfma_f32_16x16x32_bf16 v[126:129], v[134:137], v[160:163], v[126:129]
	v_mfma_f32_16x16x32_bf16 v[122:125], v[148:151], v[160:163], v[122:125]
	v_mfma_f32_16x16x32_bf16 v[118:121], v[134:137], v[168:171], v[118:121]
	v_mfma_f32_16x16x32_bf16 v[106:109], v[148:151], v[168:171], v[106:109]
	v_mfma_f32_16x16x32_bf16 v[102:105], v[134:137], v[176:179], v[102:105]
	v_mfma_f32_16x16x32_bf16 v[90:93], v[148:151], v[176:179], v[90:93]
	v_mfma_f32_16x16x32_bf16 v[86:89], v[134:137], v[184:187], v[86:89]
	v_mfma_f32_16x16x32_bf16 v[74:77], v[148:151], v[184:187], v[74:77]
	s_barrier
	s_add_i32 s86, 0, 0x14000
	v_add_u32_e32 v196, s86, v157
	s_add_i32 s22, s85, s50
	ds_read_b128 v[188:191], v196
	ds_read_b128 v[192:195], v196 offset:1024
	ds_read_b128 v[208:211], v196 offset:2048
	ds_read_b128 v[212:215], v196 offset:3072
	v_lshl_add_u64 v[196:197], s[40:41], 0, v[16:17]
	s_mov_b32 m0, s22
	v_lshl_add_u64 v[216:217], s[40:41], 0, v[142:143]
	global_load_lds_dwordx4 v[196:197], off
	s_add_i32 m0, s22, 0x2000
	s_nop 0
	global_load_lds_dwordx4 v[216:217], off
	s_waitcnt vmcnt(10)
	s_barrier
	s_waitcnt lgkmcnt(0)
	s_waitcnt lgkmcnt(0)
	v_mfma_f32_16x16x32_bf16 v[114:117], v[188:191], v[152:155], v[114:117]
	v_mfma_f32_16x16x32_bf16 v[110:113], v[208:211], v[152:155], v[110:113]
	v_mfma_f32_16x16x32_bf16 v[98:101], v[188:191], v[164:167], v[98:101]
	v_mfma_f32_16x16x32_bf16 v[94:97], v[208:211], v[164:167], v[94:97]
	v_mfma_f32_16x16x32_bf16 v[82:85], v[188:191], v[172:175], v[82:85]
	v_mfma_f32_16x16x32_bf16 v[78:81], v[208:211], v[172:175], v[78:81]
	v_mfma_f32_16x16x32_bf16 v[70:73], v[188:191], v[180:183], v[70:73]
	v_mfma_f32_16x16x32_bf16 v[66:69], v[208:211], v[180:183], v[66:69]
	v_mfma_f32_16x16x32_bf16 v[114:117], v[192:195], v[160:163], v[114:117]
	v_mfma_f32_16x16x32_bf16 v[110:113], v[212:215], v[160:163], v[110:113]
	v_mfma_f32_16x16x32_bf16 v[98:101], v[192:195], v[168:171], v[98:101]
	v_mfma_f32_16x16x32_bf16 v[94:97], v[212:215], v[168:171], v[94:97]
	v_mfma_f32_16x16x32_bf16 v[82:85], v[192:195], v[176:179], v[82:85]
	v_mfma_f32_16x16x32_bf16 v[78:81], v[212:215], v[176:179], v[78:81]
	v_mfma_f32_16x16x32_bf16 v[70:73], v[192:195], v[184:187], v[70:73]
	v_mfma_f32_16x16x32_bf16 v[66:69], v[212:215], v[184:187], v[66:69]
	s_mov_b32 m0, s54
	v_lshl_add_u64 v[218:219], s[42:43], 0, v[16:17]
	s_barrier
	ds_read_b128 v[152:155], v159 offset:16384
	ds_read_b128 v[160:163], v159 offset:17408
	ds_read_b128 v[164:167], v159 offset:18432
	ds_read_b128 v[168:171], v159 offset:19456
	ds_read_b128 v[172:175], v159 offset:20480
	ds_read_b128 v[176:179], v159 offset:21504
	ds_read_b128 v[180:183], v159 offset:22528
	ds_read_b128 v[184:187], v159 offset:23552
	global_load_lds_dwordx4 v[218:219], off
	v_lshl_add_u64 v[220:221], s[42:43], 0, v[142:143]
	s_mov_b32 m0, s55
	s_nop 0
	global_load_lds_dwordx4 v[220:221], off
	s_barrier
	s_waitcnt lgkmcnt(0)
	s_waitcnt lgkmcnt(0)
	v_mfma_f32_16x16x32_bf16 v[62:65], v[130:133], v[152:155], v[62:65]
	v_mfma_f32_16x16x32_bf16 v[58:61], v[138:141], v[152:155], v[58:61]
	v_mfma_f32_16x16x32_bf16 v[54:57], v[130:133], v[164:167], v[54:57]
	v_mfma_f32_16x16x32_bf16 v[50:53], v[138:141], v[164:167], v[50:53]
	v_mfma_f32_16x16x32_bf16 v[46:49], v[130:133], v[172:175], v[46:49]
	v_mfma_f32_16x16x32_bf16 v[38:41], v[138:141], v[172:175], v[38:41]
	v_mfma_f32_16x16x32_bf16 v[30:33], v[130:133], v[180:183], v[30:33]
	v_mfma_f32_16x16x32_bf16 v[18:21], v[138:141], v[180:183], v[18:21]
	v_mfma_f32_16x16x32_bf16 v[62:65], v[134:137], v[160:163], v[62:65]
	v_mfma_f32_16x16x32_bf16 v[58:61], v[148:151], v[160:163], v[58:61]
	v_mfma_f32_16x16x32_bf16 v[54:57], v[134:137], v[168:171], v[54:57]
	v_mfma_f32_16x16x32_bf16 v[50:53], v[148:151], v[168:171], v[50:53]
	v_mfma_f32_16x16x32_bf16 v[46:49], v[134:137], v[176:179], v[46:49]
	v_mfma_f32_16x16x32_bf16 v[38:41], v[148:151], v[176:179], v[38:41]
	v_mfma_f32_16x16x32_bf16 v[30:33], v[134:137], v[184:187], v[30:33]
	v_mfma_f32_16x16x32_bf16 v[18:21], v[148:151], v[184:187], v[18:21]
	s_barrier
	s_add_u32 s22, s40, 0xb0000
	s_addc_u32 s23, s41, 0
	s_add_i32 s85, s86, s50
	v_lshl_add_u64 v[130:131], s[22:23], 0, v[16:17]
	s_mov_b32 m0, s85
	s_nop 0
	global_load_lds_dwordx4 v[130:131], off
	v_lshl_add_u64 v[130:131], s[22:23], 0, v[142:143]
	s_add_i32 m0, s85, 0x2000
	s_nop 0
	global_load_lds_dwordx4 v[130:131], off
	s_waitcnt vmcnt(10)
	s_barrier
	v_mfma_f32_16x16x32_bf16 v[42:45], v[188:191], v[152:155], v[42:45]
	v_mfma_f32_16x16x32_bf16 v[34:37], v[208:211], v[152:155], v[34:37]
	v_mfma_f32_16x16x32_bf16 v[26:29], v[188:191], v[164:167], v[26:29]
	v_mfma_f32_16x16x32_bf16 v[22:25], v[208:211], v[164:167], v[22:25]
	v_mfma_f32_16x16x32_bf16 v[12:15], v[188:191], v[172:175], v[12:15]
	v_mfma_f32_16x16x32_bf16 v[8:11], v[208:211], v[172:175], v[8:11]
	v_mfma_f32_16x16x32_bf16 v[4:7], v[188:191], v[180:183], v[4:7]
	v_mfma_f32_16x16x32_bf16 v[0:3], v[208:211], v[180:183], v[0:3]
	v_mfma_f32_16x16x32_bf16 v[42:45], v[192:195], v[160:163], v[42:45]
	v_mfma_f32_16x16x32_bf16 v[34:37], v[212:215], v[160:163], v[34:37]
	v_mfma_f32_16x16x32_bf16 v[26:29], v[192:195], v[168:171], v[26:29]
	v_mfma_f32_16x16x32_bf16 v[22:25], v[212:215], v[168:171], v[22:25]
	v_mfma_f32_16x16x32_bf16 v[12:15], v[192:195], v[176:179], v[12:15]
	v_mfma_f32_16x16x32_bf16 v[8:11], v[212:215], v[176:179], v[8:11]
	v_mfma_f32_16x16x32_bf16 v[4:7], v[192:195], v[184:187], v[4:7]
	v_mfma_f32_16x16x32_bf16 v[0:3], v[212:215], v[184:187], v[0:3]
	s_add_i32 s85, 0, 0x18000
	v_add_u32_e32 v148, s85, v157
	s_barrier
	ds_read_b128 v[130:133], v148
	ds_read_b128 v[134:137], v148 offset:1024
	ds_read_b128 v[138:141], v148 offset:2048
	ds_read_b128 v[148:151], v148 offset:3072
	s_add_u32 s22, s42, 0xb0000
	s_addc_u32 s23, s43, 0
	s_mov_b32 m0, s56
	v_lshl_add_u64 v[188:189], s[22:23], 0, v[16:17]
	ds_read_b128 v[152:155], v159 offset:32768
	ds_read_b128 v[160:163], v159 offset:33792
	ds_read_b128 v[164:167], v159 offset:34816
	ds_read_b128 v[168:171], v159 offset:35840
	ds_read_b128 v[172:175], v159 offset:36864
	ds_read_b128 v[176:179], v159 offset:37888
	ds_read_b128 v[180:183], v159 offset:38912
	ds_read_b128 v[184:187], v159 offset:39936
	global_load_lds_dwordx4 v[188:189], off
	v_lshl_add_u64 v[188:189], s[22:23], 0, v[142:143]
	s_mov_b32 m0, s57
	s_nop 0
	global_load_lds_dwordx4 v[188:189], off
	s_waitcnt lgkmcnt(8)
	s_waitcnt vmcnt(10)
	s_barrier
	s_waitcnt lgkmcnt(0)
	s_waitcnt lgkmcnt(0)
	v_mfma_f32_16x16x32_bf16 v[126:129], v[130:133], v[152:155], v[126:129]
	v_mfma_f32_16x16x32_bf16 v[122:125], v[138:141], v[152:155], v[122:125]
	v_mfma_f32_16x16x32_bf16 v[118:121], v[130:133], v[164:167], v[118:121]
	v_mfma_f32_16x16x32_bf16 v[106:109], v[138:141], v[164:167], v[106:109]
	v_mfma_f32_16x16x32_bf16 v[102:105], v[130:133], v[172:175], v[102:105]
	v_mfma_f32_16x16x32_bf16 v[90:93], v[138:141], v[172:175], v[90:93]
	v_mfma_f32_16x16x32_bf16 v[86:89], v[130:133], v[180:183], v[86:89]
	v_mfma_f32_16x16x32_bf16 v[74:77], v[138:141], v[180:183], v[74:77]
	v_mfma_f32_16x16x32_bf16 v[126:129], v[134:137], v[160:163], v[126:129]
	v_mfma_f32_16x16x32_bf16 v[122:125], v[148:151], v[160:163], v[122:125]
	v_mfma_f32_16x16x32_bf16 v[118:121], v[134:137], v[168:171], v[118:121]
	v_mfma_f32_16x16x32_bf16 v[106:109], v[148:151], v[168:171], v[106:109]
	v_mfma_f32_16x16x32_bf16 v[102:105], v[134:137], v[176:179], v[102:105]
	v_mfma_f32_16x16x32_bf16 v[90:93], v[148:151], v[176:179], v[90:93]
	v_mfma_f32_16x16x32_bf16 v[86:89], v[134:137], v[184:187], v[86:89]
	v_mfma_f32_16x16x32_bf16 v[74:77], v[148:151], v[184:187], v[74:77]
	s_barrier
	s_add_i32 s42, 0, 0x1c000
	s_add_i32 s22, s85, s50
	v_add_u32_e32 v212, s42, v157
	v_lshl_add_u64 v[196:197], v[196:197], 0, s[10:11]
	s_mov_b32 m0, s22
	ds_read_b128 v[188:191], v212
	ds_read_b128 v[192:195], v212 offset:1024
	ds_read_b128 v[208:211], v212 offset:2048
	ds_read_b128 v[212:215], v212 offset:3072
	global_load_lds_dwordx4 v[196:197], off
	v_lshl_add_u64 v[196:197], v[216:217], 0, s[10:11]
	s_add_i32 m0, s22, 0x2000
	s_nop 0
	global_load_lds_dwordx4 v[196:197], off
	s_waitcnt vmcnt(10)
	s_barrier
	s_waitcnt lgkmcnt(0)
	s_waitcnt lgkmcnt(0)
	v_mfma_f32_16x16x32_bf16 v[114:117], v[188:191], v[152:155], v[114:117]
	v_mfma_f32_16x16x32_bf16 v[110:113], v[208:211], v[152:155], v[110:113]
	v_mfma_f32_16x16x32_bf16 v[98:101], v[188:191], v[164:167], v[98:101]
	v_mfma_f32_16x16x32_bf16 v[94:97], v[208:211], v[164:167], v[94:97]
	v_mfma_f32_16x16x32_bf16 v[82:85], v[188:191], v[172:175], v[82:85]
	v_mfma_f32_16x16x32_bf16 v[78:81], v[208:211], v[172:175], v[78:81]
	v_mfma_f32_16x16x32_bf16 v[70:73], v[188:191], v[180:183], v[70:73]
	v_mfma_f32_16x16x32_bf16 v[66:69], v[208:211], v[180:183], v[66:69]
	v_mfma_f32_16x16x32_bf16 v[114:117], v[192:195], v[160:163], v[114:117]
	v_mfma_f32_16x16x32_bf16 v[110:113], v[212:215], v[160:163], v[110:113]
	v_mfma_f32_16x16x32_bf16 v[98:101], v[192:195], v[168:171], v[98:101]
	v_mfma_f32_16x16x32_bf16 v[94:97], v[212:215], v[168:171], v[94:97]
	v_mfma_f32_16x16x32_bf16 v[82:85], v[192:195], v[176:179], v[82:85]
	v_mfma_f32_16x16x32_bf16 v[78:81], v[212:215], v[176:179], v[78:81]
	v_mfma_f32_16x16x32_bf16 v[70:73], v[192:195], v[184:187], v[70:73]
	v_mfma_f32_16x16x32_bf16 v[66:69], v[212:215], v[184:187], v[66:69]
	s_mov_b32 m0, s58
	v_lshl_add_u64 v[196:197], v[218:219], 0, s[10:11]
	s_barrier
	ds_read_b128 v[152:155], v159 offset:49152
	ds_read_b128 v[160:163], v159 offset:50176
	ds_read_b128 v[164:167], v159 offset:51200
	ds_read_b128 v[168:171], v159 offset:52224
	ds_read_b128 v[172:175], v159 offset:53248
	ds_read_b128 v[176:179], v159 offset:54272
	ds_read_b128 v[180:183], v159 offset:55296
	ds_read_b128 v[184:187], v159 offset:56320
	global_load_lds_dwordx4 v[196:197], off
	v_lshl_add_u64 v[196:197], v[220:221], 0, s[10:11]
	s_mov_b32 m0, s59
	s_nop 0
	global_load_lds_dwordx4 v[196:197], off
	s_barrier
	s_waitcnt lgkmcnt(0)
	s_waitcnt lgkmcnt(0)
	v_mfma_f32_16x16x32_bf16 v[62:65], v[130:133], v[152:155], v[62:65]
	v_mfma_f32_16x16x32_bf16 v[58:61], v[138:141], v[152:155], v[58:61]
	v_mfma_f32_16x16x32_bf16 v[54:57], v[130:133], v[164:167], v[54:57]
	v_mfma_f32_16x16x32_bf16 v[50:53], v[138:141], v[164:167], v[50:53]
	v_mfma_f32_16x16x32_bf16 v[46:49], v[130:133], v[172:175], v[46:49]
	v_mfma_f32_16x16x32_bf16 v[38:41], v[138:141], v[172:175], v[38:41]
	v_mfma_f32_16x16x32_bf16 v[30:33], v[130:133], v[180:183], v[30:33]
	v_mfma_f32_16x16x32_bf16 v[18:21], v[138:141], v[180:183], v[18:21]
	v_mfma_f32_16x16x32_bf16 v[62:65], v[134:137], v[160:163], v[62:65]
	v_mfma_f32_16x16x32_bf16 v[58:61], v[148:151], v[160:163], v[58:61]
	v_mfma_f32_16x16x32_bf16 v[54:57], v[134:137], v[168:171], v[54:57]
	v_mfma_f32_16x16x32_bf16 v[50:53], v[148:151], v[168:171], v[50:53]
	v_mfma_f32_16x16x32_bf16 v[46:49], v[134:137], v[176:179], v[46:49]
	v_mfma_f32_16x16x32_bf16 v[38:41], v[148:151], v[176:179], v[38:41]
	v_mfma_f32_16x16x32_bf16 v[30:33], v[134:137], v[184:187], v[30:33]
	v_mfma_f32_16x16x32_bf16 v[18:21], v[148:151], v[184:187], v[18:21]
	s_barrier
	s_add_u32 s22, s40, 0xb0080
	s_addc_u32 s23, s41, 0
	s_add_i32 s40, s42, s50
	v_lshl_add_u64 v[130:131], s[22:23], 0, v[16:17]
	s_mov_b32 m0, s40
	s_nop 0
	global_load_lds_dwordx4 v[130:131], off
	v_lshl_add_u64 v[130:131], s[22:23], 0, v[142:143]
	s_add_i32 m0, s40, 0x2000
	s_nop 0
	global_load_lds_dwordx4 v[130:131], off
	s_waitcnt vmcnt(10)
	s_barrier
	v_mfma_f32_16x16x32_bf16 v[42:45], v[188:191], v[152:155], v[42:45]
	v_mfma_f32_16x16x32_bf16 v[34:37], v[208:211], v[152:155], v[34:37]
	v_mfma_f32_16x16x32_bf16 v[26:29], v[188:191], v[164:167], v[26:29]
	v_mfma_f32_16x16x32_bf16 v[22:25], v[208:211], v[164:167], v[22:25]
	v_mfma_f32_16x16x32_bf16 v[12:15], v[188:191], v[172:175], v[12:15]
	v_mfma_f32_16x16x32_bf16 v[8:11], v[208:211], v[172:175], v[8:11]
	v_mfma_f32_16x16x32_bf16 v[4:7], v[188:191], v[180:183], v[4:7]
	v_mfma_f32_16x16x32_bf16 v[0:3], v[208:211], v[180:183], v[0:3]
	v_mfma_f32_16x16x32_bf16 v[42:45], v[192:195], v[160:163], v[42:45]
	v_mfma_f32_16x16x32_bf16 v[34:37], v[212:215], v[160:163], v[34:37]
	v_mfma_f32_16x16x32_bf16 v[26:29], v[192:195], v[168:171], v[26:29]
	v_mfma_f32_16x16x32_bf16 v[22:25], v[212:215], v[168:171], v[22:25]
	v_mfma_f32_16x16x32_bf16 v[12:15], v[192:195], v[176:179], v[12:15]
	v_mfma_f32_16x16x32_bf16 v[8:11], v[212:215], v[176:179], v[8:11]
	v_mfma_f32_16x16x32_bf16 v[4:7], v[192:195], v[184:187], v[4:7]
	v_mfma_f32_16x16x32_bf16 v[0:3], v[212:215], v[184:187], v[0:3]
	s_add_i32 s84, s84, 2
	s_add_u32 s34, s34, 0x100
	s_addc_u32 s79, s79, 0
	s_cmp_gt_u32 s84, 41
	s_mov_b64 s[22:23], s[28:29]
	s_barrier
	s_cbranch_scc0 .LBB0_133
	v_lshl_or_b32 v132, s12, 8, v158
	v_lshl_add_u32 v130, s2, 8, v156
	v_ashrrev_i32_e32 v133, 31, v132
	v_lshlrev_b64 v[148:149], 2, v[132:133]
	v_ashrrev_i32_e32 v131, 31, v130
	v_lshlrev_b64 v[152:153], 12, v[130:131]
	v_lshl_add_u64 v[150:151], s[4:5], 0, v[148:149]
	v_lshl_add_u64 v[154:155], v[150:151], 0, v[152:153]
	s_mov_b64 s[22:23], 0x10000
	v_lshl_add_u64 v[196:197], v[154:155], 0, s[22:23]
	s_mov_b64 s[22:23], 0x20000
	v_lshl_add_u64 v[224:225], v[154:155], 0, s[22:23]
	s_mov_b64 s[22:23], 0x30000
	v_lshl_add_u64 v[226:227], v[154:155], 0, s[22:23]
	s_mov_b64 s[22:23], 0x80000
	v_lshl_add_u64 v[240:241], v[154:155], 0, s[22:23]
	s_mov_b64 s[22:23], 0x90000
	v_lshl_add_u64 v[242:243], v[154:155], 0, s[22:23]
	s_mov_b64 s[22:23], 0xa0000
	v_lshl_add_u64 v[244:245], v[154:155], 0, s[22:23]
	s_mov_b64 s[22:23], 0xb0000
	v_lshl_add_u64 v[246:247], v[154:155], 0, s[22:23]
	s_sub_u32 s100, s14, s4
	s_subb_u32 s101, s15, s5
	global_load_dwordx4 v[160:163], v[154:155], off
	global_load_dwordx4 v[164:167], v[154:155], off offset:64
	global_load_dwordx4 v[168:171], v[154:155], off offset:512
	global_load_dwordx4 v[172:175], v[154:155], off offset:576
	global_load_dwordx4 v[176:179], v[196:197], off
	global_load_dwordx4 v[180:183], v[196:197], off offset:64
	global_load_dwordx4 v[184:187], v[196:197], off offset:512
	global_load_dwordx4 v[188:191], v[196:197], off offset:576
	global_load_dwordx4 v[192:195], v[224:225], off
	global_load_dwordx4 v[208:211], v[224:225], off offset:64
	global_load_dwordx4 v[212:215], v[224:225], off offset:512
	global_load_dwordx4 v[216:219], v[224:225], off offset:576
	global_load_dwordx4 v[220:223], v[226:227], off
	global_load_dwordx4 v[138:141], v[226:227], off offset:64
	global_load_dwordx4 v[134:137], v[226:227], off offset:512
	global_load_dwordx4 v[130:133], v[226:227], off offset:576
	s_waitcnt vmcnt(12)
	v_pk_fma_f32 v[126:127], v[126:127], 0.5, v[160:161] op_sel_hi:[1,0,1]
	v_pk_fma_f32 v[128:129], v[128:129], 0.5, v[162:163] op_sel_hi:[1,0,1]
	v_pk_fma_f32 v[122:123], v[122:123], 0.5, v[164:165] op_sel_hi:[1,0,1]
	v_pk_fma_f32 v[124:125], v[124:125], 0.5, v[166:167] op_sel_hi:[1,0,1]
	v_pk_fma_f32 v[114:115], v[114:115], 0.5, v[168:169] op_sel_hi:[1,0,1]
	v_pk_fma_f32 v[116:117], v[116:117], 0.5, v[170:171] op_sel_hi:[1,0,1]
	v_pk_fma_f32 v[110:111], v[110:111], 0.5, v[172:173] op_sel_hi:[1,0,1]
	v_pk_fma_f32 v[112:113], v[112:113], 0.5, v[174:175] op_sel_hi:[1,0,1]
	s_waitcnt vmcnt(8)
	v_pk_fma_f32 v[118:119], v[118:119], 0.5, v[176:177] op_sel_hi:[1,0,1]
	v_pk_fma_f32 v[120:121], v[120:121], 0.5, v[178:179] op_sel_hi:[1,0,1]
	v_pk_fma_f32 v[106:107], v[106:107], 0.5, v[180:181] op_sel_hi:[1,0,1]
	v_pk_fma_f32 v[108:109], v[108:109], 0.5, v[182:183] op_sel_hi:[1,0,1]
	v_pk_fma_f32 v[98:99], v[98:99], 0.5, v[184:185] op_sel_hi:[1,0,1]
	v_pk_fma_f32 v[100:101], v[100:101], 0.5, v[186:187] op_sel_hi:[1,0,1]
	v_pk_fma_f32 v[94:95], v[94:95], 0.5, v[188:189] op_sel_hi:[1,0,1]
	v_pk_fma_f32 v[96:97], v[96:97], 0.5, v[190:191] op_sel_hi:[1,0,1]
	s_waitcnt vmcnt(4)
	v_pk_fma_f32 v[102:103], v[102:103], 0.5, v[192:193] op_sel_hi:[1,0,1]
	v_pk_fma_f32 v[104:105], v[104:105], 0.5, v[194:195] op_sel_hi:[1,0,1]
	v_pk_fma_f32 v[90:91], v[90:91], 0.5, v[208:209] op_sel_hi:[1,0,1]
	v_pk_fma_f32 v[92:93], v[92:93], 0.5, v[210:211] op_sel_hi:[1,0,1]
	v_pk_fma_f32 v[82:83], v[82:83], 0.5, v[212:213] op_sel_hi:[1,0,1]
	v_pk_fma_f32 v[84:85], v[84:85], 0.5, v[214:215] op_sel_hi:[1,0,1]
	v_pk_fma_f32 v[78:79], v[78:79], 0.5, v[216:217] op_sel_hi:[1,0,1]
	v_pk_fma_f32 v[80:81], v[80:81], 0.5, v[218:219] op_sel_hi:[1,0,1]
	s_waitcnt vmcnt(0)
	v_pk_fma_f32 v[86:87], v[86:87], 0.5, v[220:221] op_sel_hi:[1,0,1]
	v_pk_fma_f32 v[88:89], v[88:89], 0.5, v[222:223] op_sel_hi:[1,0,1]
	v_pk_fma_f32 v[74:75], v[74:75], 0.5, v[138:139] op_sel_hi:[1,0,1]
	v_pk_fma_f32 v[76:77], v[76:77], 0.5, v[140:141] op_sel_hi:[1,0,1]
	v_pk_fma_f32 v[70:71], v[70:71], 0.5, v[134:135] op_sel_hi:[1,0,1]
	v_pk_fma_f32 v[72:73], v[72:73], 0.5, v[136:137] op_sel_hi:[1,0,1]
	v_pk_fma_f32 v[66:67], v[66:67], 0.5, v[130:131] op_sel_hi:[1,0,1]
	v_pk_fma_f32 v[68:69], v[68:69], 0.5, v[132:133] op_sel_hi:[1,0,1]
	global_load_dwordx4 v[160:163], v[240:241], off
	global_load_dwordx4 v[164:167], v[240:241], off offset:64
	global_load_dwordx4 v[168:171], v[240:241], off offset:512
	global_load_dwordx4 v[172:175], v[240:241], off offset:576
	global_load_dwordx4 v[176:179], v[242:243], off
	global_load_dwordx4 v[180:183], v[242:243], off offset:64
	global_load_dwordx4 v[184:187], v[242:243], off offset:512
	global_load_dwordx4 v[188:191], v[242:243], off offset:576
	global_load_dwordx4 v[192:195], v[244:245], off
	global_load_dwordx4 v[208:211], v[244:245], off offset:64
	global_load_dwordx4 v[212:215], v[244:245], off offset:512
	global_load_dwordx4 v[216:219], v[244:245], off offset:576
	global_load_dwordx4 v[220:223], v[246:247], off
	global_load_dwordx4 v[138:141], v[246:247], off offset:64
	global_load_dwordx4 v[134:137], v[246:247], off offset:512
	global_load_dwordx4 v[130:133], v[246:247], off offset:576
	v_lshl_add_u64 v[154:155], v[154:155], 0, s[100:101]
	v_lshl_add_u64 v[196:197], v[196:197], 0, s[100:101]
	v_lshl_add_u64 v[224:225], v[224:225], 0, s[100:101]
	v_lshl_add_u64 v[226:227], v[226:227], 0, s[100:101]
	global_store_dwordx4 v[154:155], v[126:129], off
	global_store_dwordx4 v[154:155], v[122:125], off offset:64
	global_store_dwordx4 v[154:155], v[114:117], off offset:512
	global_store_dwordx4 v[154:155], v[110:113], off offset:576
	global_store_dwordx4 v[196:197], v[118:121], off
	global_store_dwordx4 v[196:197], v[106:109], off offset:64
	global_store_dwordx4 v[196:197], v[98:101], off offset:512
	global_store_dwordx4 v[196:197], v[94:97], off offset:576
	global_store_dwordx4 v[224:225], v[102:105], off
	global_store_dwordx4 v[224:225], v[90:93], off offset:64
	global_store_dwordx4 v[224:225], v[82:85], off offset:512
	global_store_dwordx4 v[224:225], v[78:81], off offset:576
	global_store_dwordx4 v[226:227], v[86:89], off
	global_store_dwordx4 v[226:227], v[74:77], off offset:64
	global_store_dwordx4 v[226:227], v[70:73], off offset:512
	global_store_dwordx4 v[226:227], v[66:69], off offset:576
	s_waitcnt vmcnt(0)
	v_pk_fma_f32 v[62:63], v[62:63], 0.5, v[160:161] op_sel_hi:[1,0,1]
	v_pk_fma_f32 v[64:65], v[64:65], 0.5, v[162:163] op_sel_hi:[1,0,1]
	v_pk_fma_f32 v[58:59], v[58:59], 0.5, v[164:165] op_sel_hi:[1,0,1]
	v_pk_fma_f32 v[60:61], v[60:61], 0.5, v[166:167] op_sel_hi:[1,0,1]
	v_pk_fma_f32 v[42:43], v[42:43], 0.5, v[168:169] op_sel_hi:[1,0,1]
	v_pk_fma_f32 v[44:45], v[44:45], 0.5, v[170:171] op_sel_hi:[1,0,1]
	v_pk_fma_f32 v[34:35], v[34:35], 0.5, v[172:173] op_sel_hi:[1,0,1]
	v_pk_fma_f32 v[36:37], v[36:37], 0.5, v[174:175] op_sel_hi:[1,0,1]
	v_pk_fma_f32 v[54:55], v[54:55], 0.5, v[176:177] op_sel_hi:[1,0,1]
	v_pk_fma_f32 v[56:57], v[56:57], 0.5, v[178:179] op_sel_hi:[1,0,1]
	v_pk_fma_f32 v[50:51], v[50:51], 0.5, v[180:181] op_sel_hi:[1,0,1]
	v_pk_fma_f32 v[52:53], v[52:53], 0.5, v[182:183] op_sel_hi:[1,0,1]
	v_pk_fma_f32 v[26:27], v[26:27], 0.5, v[184:185] op_sel_hi:[1,0,1]
	v_pk_fma_f32 v[28:29], v[28:29], 0.5, v[186:187] op_sel_hi:[1,0,1]
	v_pk_fma_f32 v[22:23], v[22:23], 0.5, v[188:189] op_sel_hi:[1,0,1]
	v_pk_fma_f32 v[24:25], v[24:25], 0.5, v[190:191] op_sel_hi:[1,0,1]
	v_pk_fma_f32 v[46:47], v[46:47], 0.5, v[192:193] op_sel_hi:[1,0,1]
	v_pk_fma_f32 v[48:49], v[48:49], 0.5, v[194:195] op_sel_hi:[1,0,1]
	v_pk_fma_f32 v[38:39], v[38:39], 0.5, v[208:209] op_sel_hi:[1,0,1]
	v_pk_fma_f32 v[40:41], v[40:41], 0.5, v[210:211] op_sel_hi:[1,0,1]
	v_pk_fma_f32 v[12:13], v[12:13], 0.5, v[212:213] op_sel_hi:[1,0,1]
	v_pk_fma_f32 v[14:15], v[14:15], 0.5, v[214:215] op_sel_hi:[1,0,1]
	v_pk_fma_f32 v[8:9], v[8:9], 0.5, v[216:217] op_sel_hi:[1,0,1]
	v_pk_fma_f32 v[10:11], v[10:11], 0.5, v[218:219] op_sel_hi:[1,0,1]
	v_pk_fma_f32 v[30:31], v[30:31], 0.5, v[220:221] op_sel_hi:[1,0,1]
	v_pk_fma_f32 v[32:33], v[32:33], 0.5, v[222:223] op_sel_hi:[1,0,1]
	v_pk_fma_f32 v[18:19], v[18:19], 0.5, v[138:139] op_sel_hi:[1,0,1]
	v_pk_fma_f32 v[20:21], v[20:21], 0.5, v[140:141] op_sel_hi:[1,0,1]
	v_pk_fma_f32 v[4:5], v[4:5], 0.5, v[134:135] op_sel_hi:[1,0,1]
	v_pk_fma_f32 v[6:7], v[6:7], 0.5, v[136:137] op_sel_hi:[1,0,1]
	v_pk_fma_f32 v[0:1], v[0:1], 0.5, v[130:131] op_sel_hi:[1,0,1]
	v_pk_fma_f32 v[2:3], v[2:3], 0.5, v[132:133] op_sel_hi:[1,0,1]
	v_lshl_add_u64 v[240:241], v[240:241], 0, s[100:101]
	v_lshl_add_u64 v[242:243], v[242:243], 0, s[100:101]
	v_lshl_add_u64 v[244:245], v[244:245], 0, s[100:101]
	v_lshl_add_u64 v[246:247], v[246:247], 0, s[100:101]
	global_store_dwordx4 v[240:241], v[62:65], off
	global_store_dwordx4 v[240:241], v[58:61], off offset:64
	global_store_dwordx4 v[240:241], v[42:45], off offset:512
	global_store_dwordx4 v[240:241], v[34:37], off offset:576
	global_store_dwordx4 v[242:243], v[54:57], off
	global_store_dwordx4 v[242:243], v[50:53], off offset:64
	global_store_dwordx4 v[242:243], v[26:29], off offset:512
	global_store_dwordx4 v[242:243], v[22:25], off offset:576
	global_store_dwordx4 v[244:245], v[46:49], off
	global_store_dwordx4 v[244:245], v[38:41], off offset:64
	global_store_dwordx4 v[244:245], v[12:15], off offset:512
	global_store_dwordx4 v[244:245], v[8:11], off offset:576
	global_store_dwordx4 v[246:247], v[30:33], off
	global_store_dwordx4 v[246:247], v[18:21], off offset:64
	global_store_dwordx4 v[246:247], v[4:7], off offset:512
	global_store_dwordx4 v[246:247], v[0:3], off offset:576
	s_and_b64 vcc, exec, s[38:39]
	s_mov_b32 s12, s82
	s_mov_b32 s2, s83
	s_mov_b64 s[28:29], s[18:19]
	s_mov_b64 s[22:23], s[16:17]
	s_mov_b32 s86, 0x38c0000
	s_cbranch_vccz .LBB0_122
	s_waitcnt vmcnt(0)
	s_cmpk_gt_u32 s48, 0xff
	s_cbranch_scc1 .LBB0_137
	s_barrier

.LBB0_174:
	s_add_u32 s40, s22, 0x100
	s_addc_u32 s41, s23, 0
	s_add_i32 s83, 0, 0x10000
	v_add_u32_e32 v148, s83, v157
	ds_read_b128 v[130:133], v148
	ds_read_b128 v[134:137], v148 offset:1024
	ds_read_b128 v[138:141], v148 offset:2048
	ds_read_b128 v[148:151], v148 offset:3072
	s_cmp_eq_u32 s82, 12
	s_cselect_b32 s49, s9, s41
	s_cselect_b32 s48, s12, s40
	s_cselect_b32 s43, s5, s79
	s_cselect_b32 s42, s34, s61
	v_lshl_add_u64 v[188:189], s[22:23], 0, v[146:147]
	s_add_i32 m0, s19, 0xc000
	ds_read_b128 v[152:155], v159
	ds_read_b128 v[160:163], v159 offset:1024
	ds_read_b128 v[164:167], v159 offset:2048
	ds_read_b128 v[168:171], v159 offset:3072
	ds_read_b128 v[172:175], v159 offset:4096
	ds_read_b128 v[176:179], v159 offset:5120
	ds_read_b128 v[180:183], v159 offset:6144
	ds_read_b128 v[184:187], v159 offset:7168
	global_load_lds_dwordx4 v[188:189], off
	v_lshl_add_u64 v[188:189], s[22:23], 0, v[144:145]
	s_add_i32 m0, s19, 0xe000
	s_nop 0
	global_load_lds_dwordx4 v[188:189], off
	s_waitcnt lgkmcnt(8)
	s_waitcnt vmcnt(10)
	s_barrier
	s_waitcnt lgkmcnt(0)
	s_waitcnt lgkmcnt(0)
	v_mfma_f32_16x16x32_bf16 v[126:129], v[130:133], v[152:155], v[126:129]
	v_mfma_f32_16x16x32_bf16 v[122:125], v[138:141], v[152:155], v[122:125]
	v_mfma_f32_16x16x32_bf16 v[118:121], v[130:133], v[164:167], v[118:121]
	v_mfma_f32_16x16x32_bf16 v[106:109], v[138:141], v[164:167], v[106:109]
	v_mfma_f32_16x16x32_bf16 v[102:105], v[130:133], v[172:175], v[102:105]
	v_mfma_f32_16x16x32_bf16 v[90:93], v[138:141], v[172:175], v[90:93]
	v_mfma_f32_16x16x32_bf16 v[86:89], v[130:133], v[180:183], v[86:89]
	v_mfma_f32_16x16x32_bf16 v[74:77], v[138:141], v[180:183], v[74:77]
	v_mfma_f32_16x16x32_bf16 v[126:129], v[134:137], v[160:163], v[126:129]
	v_mfma_f32_16x16x32_bf16 v[122:125], v[148:151], v[160:163], v[122:125]
	v_mfma_f32_16x16x32_bf16 v[118:121], v[134:137], v[168:171], v[118:121]
	v_mfma_f32_16x16x32_bf16 v[106:109], v[148:151], v[168:171], v[106:109]
	v_mfma_f32_16x16x32_bf16 v[102:105], v[134:137], v[176:179], v[102:105]
	v_mfma_f32_16x16x32_bf16 v[90:93], v[148:151], v[176:179], v[90:93]
	v_mfma_f32_16x16x32_bf16 v[86:89], v[134:137], v[184:187], v[86:89]
	v_mfma_f32_16x16x32_bf16 v[74:77], v[148:151], v[184:187], v[74:77]
	s_barrier
	s_add_i32 s84, 0, 0x14000
	v_add_u32_e32 v196, s84, v157
	s_add_i32 s22, s83, s52
	ds_read_b128 v[188:191], v196
	ds_read_b128 v[192:195], v196 offset:1024
	ds_read_b128 v[208:211], v196 offset:2048
	ds_read_b128 v[212:215], v196 offset:3072
	v_lshl_add_u64 v[196:197], s[42:43], 0, v[16:17]
	s_mov_b32 m0, s22
	v_lshl_add_u64 v[216:217], s[42:43], 0, v[142:143]
	global_load_lds_dwordx4 v[196:197], off
	s_add_i32 m0, s22, 0x2000
	s_nop 0
	global_load_lds_dwordx4 v[216:217], off
	s_waitcnt vmcnt(10)
	s_barrier
	s_waitcnt lgkmcnt(0)
	s_waitcnt lgkmcnt(0)
	v_mfma_f32_16x16x32_bf16 v[114:117], v[188:191], v[152:155], v[114:117]
	v_mfma_f32_16x16x32_bf16 v[110:113], v[208:211], v[152:155], v[110:113]
	v_mfma_f32_16x16x32_bf16 v[98:101], v[188:191], v[164:167], v[98:101]
	v_mfma_f32_16x16x32_bf16 v[94:97], v[208:211], v[164:167], v[94:97]
	v_mfma_f32_16x16x32_bf16 v[82:85], v[188:191], v[172:175], v[82:85]
	v_mfma_f32_16x16x32_bf16 v[78:81], v[208:211], v[172:175], v[78:81]
	v_mfma_f32_16x16x32_bf16 v[70:73], v[188:191], v[180:183], v[70:73]
	v_mfma_f32_16x16x32_bf16 v[66:69], v[208:211], v[180:183], v[66:69]
	v_mfma_f32_16x16x32_bf16 v[114:117], v[192:195], v[160:163], v[114:117]
	v_mfma_f32_16x16x32_bf16 v[110:113], v[212:215], v[160:163], v[110:113]
	v_mfma_f32_16x16x32_bf16 v[98:101], v[192:195], v[168:171], v[98:101]
	v_mfma_f32_16x16x32_bf16 v[94:97], v[212:215], v[168:171], v[94:97]
	v_mfma_f32_16x16x32_bf16 v[82:85], v[192:195], v[176:179], v[82:85]
	v_mfma_f32_16x16x32_bf16 v[78:81], v[212:215], v[176:179], v[78:81]
	v_mfma_f32_16x16x32_bf16 v[70:73], v[192:195], v[184:187], v[70:73]
	v_mfma_f32_16x16x32_bf16 v[66:69], v[212:215], v[184:187], v[66:69]
	s_mov_b32 m0, s19
	v_lshl_add_u64 v[218:219], s[48:49], 0, v[16:17]
	s_barrier
	ds_read_b128 v[152:155], v159 offset:16384
	ds_read_b128 v[160:163], v159 offset:17408
	ds_read_b128 v[164:167], v159 offset:18432
	ds_read_b128 v[168:171], v159 offset:19456
	ds_read_b128 v[172:175], v159 offset:20480
	ds_read_b128 v[176:179], v159 offset:21504
	ds_read_b128 v[180:183], v159 offset:22528
	ds_read_b128 v[184:187], v159 offset:23552
	global_load_lds_dwordx4 v[218:219], off
	v_lshl_add_u64 v[220:221], s[48:49], 0, v[142:143]
	s_mov_b32 m0, s54
	s_nop 0
	global_load_lds_dwordx4 v[220:221], off
	s_barrier
	s_waitcnt lgkmcnt(0)
	s_waitcnt lgkmcnt(0)
	v_mfma_f32_16x16x32_bf16 v[62:65], v[130:133], v[152:155], v[62:65]
	v_mfma_f32_16x16x32_bf16 v[58:61], v[138:141], v[152:155], v[58:61]
	v_mfma_f32_16x16x32_bf16 v[54:57], v[130:133], v[164:167], v[54:57]
	v_mfma_f32_16x16x32_bf16 v[50:53], v[138:141], v[164:167], v[50:53]
	v_mfma_f32_16x16x32_bf16 v[46:49], v[130:133], v[172:175], v[46:49]
	v_mfma_f32_16x16x32_bf16 v[38:41], v[138:141], v[172:175], v[38:41]
	v_mfma_f32_16x16x32_bf16 v[30:33], v[130:133], v[180:183], v[30:33]
	v_mfma_f32_16x16x32_bf16 v[18:21], v[138:141], v[180:183], v[18:21]
	v_mfma_f32_16x16x32_bf16 v[62:65], v[134:137], v[160:163], v[62:65]
	v_mfma_f32_16x16x32_bf16 v[58:61], v[148:151], v[160:163], v[58:61]
	v_mfma_f32_16x16x32_bf16 v[54:57], v[134:137], v[168:171], v[54:57]
	v_mfma_f32_16x16x32_bf16 v[50:53], v[148:151], v[168:171], v[50:53]
	v_mfma_f32_16x16x32_bf16 v[46:49], v[134:137], v[176:179], v[46:49]
	v_mfma_f32_16x16x32_bf16 v[38:41], v[148:151], v[176:179], v[38:41]
	v_mfma_f32_16x16x32_bf16 v[30:33], v[134:137], v[184:187], v[30:33]
	v_mfma_f32_16x16x32_bf16 v[18:21], v[148:151], v[184:187], v[18:21]
	s_barrier
	s_add_u32 s22, s42, 0x40000
	s_addc_u32 s23, s43, 0
	s_add_i32 s83, s84, s52
	v_lshl_add_u64 v[130:131], s[22:23], 0, v[16:17]
	s_mov_b32 m0, s83
	s_nop 0
	global_load_lds_dwordx4 v[130:131], off
	v_lshl_add_u64 v[130:131], s[22:23], 0, v[142:143]
	s_add_i32 m0, s83, 0x2000
	s_nop 0
	global_load_lds_dwordx4 v[130:131], off
	s_waitcnt vmcnt(10)
	s_barrier
	v_mfma_f32_16x16x32_bf16 v[42:45], v[188:191], v[152:155], v[42:45]
	v_mfma_f32_16x16x32_bf16 v[34:37], v[208:211], v[152:155], v[34:37]
	v_mfma_f32_16x16x32_bf16 v[26:29], v[188:191], v[164:167], v[26:29]
	v_mfma_f32_16x16x32_bf16 v[22:25], v[208:211], v[164:167], v[22:25]
	v_mfma_f32_16x16x32_bf16 v[12:15], v[188:191], v[172:175], v[12:15]
	v_mfma_f32_16x16x32_bf16 v[8:11], v[208:211], v[172:175], v[8:11]
	v_mfma_f32_16x16x32_bf16 v[4:7], v[188:191], v[180:183], v[4:7]
	v_mfma_f32_16x16x32_bf16 v[0:3], v[208:211], v[180:183], v[0:3]
	v_mfma_f32_16x16x32_bf16 v[42:45], v[192:195], v[160:163], v[42:45]
	v_mfma_f32_16x16x32_bf16 v[34:37], v[212:215], v[160:163], v[34:37]
	v_mfma_f32_16x16x32_bf16 v[26:29], v[192:195], v[168:171], v[26:29]
	v_mfma_f32_16x16x32_bf16 v[22:25], v[212:215], v[168:171], v[22:25]
	v_mfma_f32_16x16x32_bf16 v[12:15], v[192:195], v[176:179], v[12:15]
	v_mfma_f32_16x16x32_bf16 v[8:11], v[212:215], v[176:179], v[8:11]
	v_mfma_f32_16x16x32_bf16 v[4:7], v[192:195], v[184:187], v[4:7]
	v_mfma_f32_16x16x32_bf16 v[0:3], v[212:215], v[184:187], v[0:3]
	s_add_i32 s83, 0, 0x18000
	v_add_u32_e32 v148, s83, v157
	s_barrier
	ds_read_b128 v[130:133], v148
	ds_read_b128 v[134:137], v148 offset:1024
	ds_read_b128 v[138:141], v148 offset:2048
	ds_read_b128 v[148:151], v148 offset:3072
	s_add_u32 s22, s48, 0x40000
	s_addc_u32 s23, s49, 0
	s_mov_b32 m0, s55
	v_lshl_add_u64 v[188:189], s[22:23], 0, v[16:17]
	ds_read_b128 v[152:155], v159 offset:32768
	ds_read_b128 v[160:163], v159 offset:33792
	ds_read_b128 v[164:167], v159 offset:34816
	ds_read_b128 v[168:171], v159 offset:35840
	ds_read_b128 v[172:175], v159 offset:36864
	ds_read_b128 v[176:179], v159 offset:37888
	ds_read_b128 v[180:183], v159 offset:38912
	ds_read_b128 v[184:187], v159 offset:39936
	global_load_lds_dwordx4 v[188:189], off
	v_lshl_add_u64 v[188:189], s[22:23], 0, v[142:143]
	s_mov_b32 m0, s56
	s_nop 0
	global_load_lds_dwordx4 v[188:189], off
	s_waitcnt lgkmcnt(8)
	s_waitcnt vmcnt(10)
	s_barrier
	s_waitcnt lgkmcnt(0)
	s_waitcnt lgkmcnt(0)
	v_mfma_f32_16x16x32_bf16 v[126:129], v[130:133], v[152:155], v[126:129]
	v_mfma_f32_16x16x32_bf16 v[122:125], v[138:141], v[152:155], v[122:125]
	v_mfma_f32_16x16x32_bf16 v[118:121], v[130:133], v[164:167], v[118:121]
	v_mfma_f32_16x16x32_bf16 v[106:109], v[138:141], v[164:167], v[106:109]
	v_mfma_f32_16x16x32_bf16 v[102:105], v[130:133], v[172:175], v[102:105]
	v_mfma_f32_16x16x32_bf16 v[90:93], v[138:141], v[172:175], v[90:93]
	v_mfma_f32_16x16x32_bf16 v[86:89], v[130:133], v[180:183], v[86:89]
	v_mfma_f32_16x16x32_bf16 v[74:77], v[138:141], v[180:183], v[74:77]
	v_mfma_f32_16x16x32_bf16 v[126:129], v[134:137], v[160:163], v[126:129]
	v_mfma_f32_16x16x32_bf16 v[122:125], v[148:151], v[160:163], v[122:125]
	v_mfma_f32_16x16x32_bf16 v[118:121], v[134:137], v[168:171], v[118:121]
	v_mfma_f32_16x16x32_bf16 v[106:109], v[148:151], v[168:171], v[106:109]
	v_mfma_f32_16x16x32_bf16 v[102:105], v[134:137], v[176:179], v[102:105]
	v_mfma_f32_16x16x32_bf16 v[90:93], v[148:151], v[176:179], v[90:93]
	v_mfma_f32_16x16x32_bf16 v[86:89], v[134:137], v[184:187], v[86:89]
	v_mfma_f32_16x16x32_bf16 v[74:77], v[148:151], v[184:187], v[74:77]
	s_barrier
	s_add_i32 s48, 0, 0x1c000
	s_add_i32 s22, s83, s52
	v_add_u32_e32 v212, s48, v157
	v_lshl_add_u64 v[196:197], v[196:197], 0, s[10:11]
	s_mov_b32 m0, s22
	ds_read_b128 v[188:191], v212
	ds_read_b128 v[192:195], v212 offset:1024
	ds_read_b128 v[208:211], v212 offset:2048
	ds_read_b128 v[212:215], v212 offset:3072
	global_load_lds_dwordx4 v[196:197], off
	v_lshl_add_u64 v[196:197], v[216:217], 0, s[10:11]
	s_add_i32 m0, s22, 0x2000
	s_nop 0
	global_load_lds_dwordx4 v[196:197], off
	s_waitcnt vmcnt(10)
	s_barrier
	s_waitcnt lgkmcnt(0)
	s_waitcnt lgkmcnt(0)
	v_mfma_f32_16x16x32_bf16 v[114:117], v[188:191], v[152:155], v[114:117]
	v_mfma_f32_16x16x32_bf16 v[110:113], v[208:211], v[152:155], v[110:113]
	v_mfma_f32_16x16x32_bf16 v[98:101], v[188:191], v[164:167], v[98:101]
	v_mfma_f32_16x16x32_bf16 v[94:97], v[208:211], v[164:167], v[94:97]
	v_mfma_f32_16x16x32_bf16 v[82:85], v[188:191], v[172:175], v[82:85]
	v_mfma_f32_16x16x32_bf16 v[78:81], v[208:211], v[172:175], v[78:81]
	v_mfma_f32_16x16x32_bf16 v[70:73], v[188:191], v[180:183], v[70:73]
	v_mfma_f32_16x16x32_bf16 v[66:69], v[208:211], v[180:183], v[66:69]
	v_mfma_f32_16x16x32_bf16 v[114:117], v[192:195], v[160:163], v[114:117]
	v_mfma_f32_16x16x32_bf16 v[110:113], v[212:215], v[160:163], v[110:113]
	v_mfma_f32_16x16x32_bf16 v[98:101], v[192:195], v[168:171], v[98:101]
	v_mfma_f32_16x16x32_bf16 v[94:97], v[212:215], v[168:171], v[94:97]
	v_mfma_f32_16x16x32_bf16 v[82:85], v[192:195], v[176:179], v[82:85]
	v_mfma_f32_16x16x32_bf16 v[78:81], v[212:215], v[176:179], v[78:81]
	v_mfma_f32_16x16x32_bf16 v[70:73], v[192:195], v[184:187], v[70:73]
	v_mfma_f32_16x16x32_bf16 v[66:69], v[212:215], v[184:187], v[66:69]
	s_mov_b32 m0, s57
	v_lshl_add_u64 v[196:197], v[218:219], 0, s[10:11]
	s_barrier
	ds_read_b128 v[152:155], v159 offset:49152
	ds_read_b128 v[160:163], v159 offset:50176
	ds_read_b128 v[164:167], v159 offset:51200
	ds_read_b128 v[168:171], v159 offset:52224
	ds_read_b128 v[172:175], v159 offset:53248
	ds_read_b128 v[176:179], v159 offset:54272
	ds_read_b128 v[180:183], v159 offset:55296
	ds_read_b128 v[184:187], v159 offset:56320
	global_load_lds_dwordx4 v[196:197], off
	v_lshl_add_u64 v[196:197], v[220:221], 0, s[10:11]
	s_mov_b32 m0, s58
	s_nop 0
	global_load_lds_dwordx4 v[196:197], off
	s_barrier
	s_waitcnt lgkmcnt(0)
	s_waitcnt lgkmcnt(0)
	v_mfma_f32_16x16x32_bf16 v[62:65], v[130:133], v[152:155], v[62:65]
	v_mfma_f32_16x16x32_bf16 v[58:61], v[138:141], v[152:155], v[58:61]
	v_mfma_f32_16x16x32_bf16 v[54:57], v[130:133], v[164:167], v[54:57]
	v_mfma_f32_16x16x32_bf16 v[50:53], v[138:141], v[164:167], v[50:53]
	v_mfma_f32_16x16x32_bf16 v[46:49], v[130:133], v[172:175], v[46:49]
	v_mfma_f32_16x16x32_bf16 v[38:41], v[138:141], v[172:175], v[38:41]
	v_mfma_f32_16x16x32_bf16 v[30:33], v[130:133], v[180:183], v[30:33]
	v_mfma_f32_16x16x32_bf16 v[18:21], v[138:141], v[180:183], v[18:21]
	v_mfma_f32_16x16x32_bf16 v[62:65], v[134:137], v[160:163], v[62:65]
	v_mfma_f32_16x16x32_bf16 v[58:61], v[148:151], v[160:163], v[58:61]
	v_mfma_f32_16x16x32_bf16 v[54:57], v[134:137], v[168:171], v[54:57]
	v_mfma_f32_16x16x32_bf16 v[50:53], v[148:151], v[168:171], v[50:53]
	v_mfma_f32_16x16x32_bf16 v[46:49], v[134:137], v[176:179], v[46:49]
	v_mfma_f32_16x16x32_bf16 v[38:41], v[148:151], v[176:179], v[38:41]
	v_mfma_f32_16x16x32_bf16 v[30:33], v[134:137], v[184:187], v[30:33]
	v_mfma_f32_16x16x32_bf16 v[18:21], v[148:151], v[184:187], v[18:21]
	s_barrier
	s_add_u32 s22, s42, 0x40080
	s_addc_u32 s23, s43, 0
	s_add_i32 s42, s48, s52
	v_lshl_add_u64 v[130:131], s[22:23], 0, v[16:17]
	s_mov_b32 m0, s42
	s_nop 0
	global_load_lds_dwordx4 v[130:131], off
	v_lshl_add_u64 v[130:131], s[22:23], 0, v[142:143]
	s_add_i32 m0, s42, 0x2000
	s_nop 0
	global_load_lds_dwordx4 v[130:131], off
	s_waitcnt vmcnt(10)
	s_barrier
	v_mfma_f32_16x16x32_bf16 v[42:45], v[188:191], v[152:155], v[42:45]
	v_mfma_f32_16x16x32_bf16 v[34:37], v[208:211], v[152:155], v[34:37]
	v_mfma_f32_16x16x32_bf16 v[26:29], v[188:191], v[164:167], v[26:29]
	v_mfma_f32_16x16x32_bf16 v[22:25], v[208:211], v[164:167], v[22:25]
	v_mfma_f32_16x16x32_bf16 v[12:15], v[188:191], v[172:175], v[12:15]
	v_mfma_f32_16x16x32_bf16 v[8:11], v[208:211], v[172:175], v[8:11]
	v_mfma_f32_16x16x32_bf16 v[4:7], v[188:191], v[180:183], v[4:7]
	v_mfma_f32_16x16x32_bf16 v[0:3], v[208:211], v[180:183], v[0:3]
	v_mfma_f32_16x16x32_bf16 v[42:45], v[192:195], v[160:163], v[42:45]
	v_mfma_f32_16x16x32_bf16 v[34:37], v[212:215], v[160:163], v[34:37]
	v_mfma_f32_16x16x32_bf16 v[26:29], v[192:195], v[168:171], v[26:29]
	v_mfma_f32_16x16x32_bf16 v[22:25], v[212:215], v[168:171], v[22:25]
	v_mfma_f32_16x16x32_bf16 v[12:15], v[192:195], v[176:179], v[12:15]
	v_mfma_f32_16x16x32_bf16 v[8:11], v[212:215], v[176:179], v[8:11]
	v_mfma_f32_16x16x32_bf16 v[4:7], v[192:195], v[184:187], v[4:7]
	v_mfma_f32_16x16x32_bf16 v[0:3], v[212:215], v[184:187], v[0:3]
	s_add_i32 s82, s82, 2
	s_add_u32 s61, s61, 0x100
	s_addc_u32 s79, s79, 0
	s_cmp_gt_u32 s82, 13
	s_mov_b64 s[22:23], s[40:41]
	s_barrier
	s_cbranch_scc0 .LBB0_174
	v_lshl_or_b32 v132, s2, 8, v158
	v_lshl_add_u32 v130, s18, 8, v156
	v_ashrrev_i32_e32 v133, 31, v132
	v_lshlrev_b64 v[148:149], 2, v[132:133]
	v_ashrrev_i32_e32 v131, 31, v130
	v_lshlrev_b64 v[152:153], 12, v[130:131]
	v_lshl_add_u64 v[150:151], s[20:21], 0, v[148:149]
	v_lshl_add_u64 v[154:155], v[150:151], 0, v[152:153]
	s_mov_b64 s[22:23], 0x10000
	v_lshl_add_u64 v[196:197], v[154:155], 0, s[22:23]
	s_mov_b64 s[22:23], 0x20000
	v_lshl_add_u64 v[224:225], v[154:155], 0, s[22:23]
	s_mov_b64 s[22:23], 0x30000
	v_lshl_add_u64 v[226:227], v[154:155], 0, s[22:23]
	s_mov_b64 s[22:23], 0x80000
	v_lshl_add_u64 v[240:241], v[154:155], 0, s[22:23]
	s_mov_b64 s[22:23], 0x90000
	v_lshl_add_u64 v[242:243], v[154:155], 0, s[22:23]
	s_mov_b64 s[22:23], 0xa0000
	v_lshl_add_u64 v[244:245], v[154:155], 0, s[22:23]
	s_mov_b64 s[22:23], 0xb0000
	v_lshl_add_u64 v[246:247], v[154:155], 0, s[22:23]
	global_load_dwordx4 v[160:163], v[154:155], off
	global_load_dwordx4 v[164:167], v[154:155], off offset:64
	global_load_dwordx4 v[168:171], v[154:155], off offset:512
	global_load_dwordx4 v[172:175], v[154:155], off offset:576
	global_load_dwordx4 v[176:179], v[196:197], off
	global_load_dwordx4 v[180:183], v[196:197], off offset:64
	global_load_dwordx4 v[184:187], v[196:197], off offset:512
	global_load_dwordx4 v[188:191], v[196:197], off offset:576
	global_load_dwordx4 v[192:195], v[224:225], off
	global_load_dwordx4 v[208:211], v[224:225], off offset:64
	global_load_dwordx4 v[212:215], v[224:225], off offset:512
	global_load_dwordx4 v[216:219], v[224:225], off offset:576
	global_load_dwordx4 v[220:223], v[226:227], off
	global_load_dwordx4 v[138:141], v[226:227], off offset:64
	global_load_dwordx4 v[134:137], v[226:227], off offset:512
	global_load_dwordx4 v[130:133], v[226:227], off offset:576
	s_waitcnt vmcnt(12)
	v_pk_add_f32 v[126:127], v[126:127], v[160:161]
	v_pk_add_f32 v[128:129], v[128:129], v[162:163]
	v_pk_add_f32 v[122:123], v[122:123], v[164:165]
	v_pk_add_f32 v[124:125], v[124:125], v[166:167]
	v_pk_add_f32 v[114:115], v[114:115], v[168:169]
	v_pk_add_f32 v[116:117], v[116:117], v[170:171]
	v_pk_add_f32 v[110:111], v[110:111], v[172:173]
	v_pk_add_f32 v[112:113], v[112:113], v[174:175]
	s_waitcnt vmcnt(8)
	v_pk_add_f32 v[118:119], v[118:119], v[176:177]
	v_pk_add_f32 v[120:121], v[120:121], v[178:179]
	v_pk_add_f32 v[106:107], v[106:107], v[180:181]
	v_pk_add_f32 v[108:109], v[108:109], v[182:183]
	v_pk_add_f32 v[98:99], v[98:99], v[184:185]
	v_pk_add_f32 v[100:101], v[100:101], v[186:187]
	v_pk_add_f32 v[94:95], v[94:95], v[188:189]
	v_pk_add_f32 v[96:97], v[96:97], v[190:191]
	s_waitcnt vmcnt(4)
	v_pk_add_f32 v[102:103], v[102:103], v[192:193]
	v_pk_add_f32 v[104:105], v[104:105], v[194:195]
	v_pk_add_f32 v[90:91], v[90:91], v[208:209]
	v_pk_add_f32 v[92:93], v[92:93], v[210:211]
	v_pk_add_f32 v[82:83], v[82:83], v[212:213]
	v_pk_add_f32 v[84:85], v[84:85], v[214:215]
	v_pk_add_f32 v[78:79], v[78:79], v[216:217]
	v_pk_add_f32 v[80:81], v[80:81], v[218:219]
	s_waitcnt vmcnt(0)
	v_pk_add_f32 v[86:87], v[86:87], v[220:221]
	v_pk_add_f32 v[88:89], v[88:89], v[222:223]
	v_pk_add_f32 v[74:75], v[74:75], v[138:139]
	v_pk_add_f32 v[76:77], v[76:77], v[140:141]
	v_pk_add_f32 v[70:71], v[70:71], v[134:135]
	v_pk_add_f32 v[72:73], v[72:73], v[136:137]
	v_pk_add_f32 v[66:67], v[66:67], v[130:131]
	v_pk_add_f32 v[68:69], v[68:69], v[132:133]
	global_load_dwordx4 v[160:163], v[240:241], off
	global_load_dwordx4 v[164:167], v[240:241], off offset:64
	global_load_dwordx4 v[168:171], v[240:241], off offset:512
	global_load_dwordx4 v[172:175], v[240:241], off offset:576
	global_load_dwordx4 v[176:179], v[242:243], off
	global_load_dwordx4 v[180:183], v[242:243], off offset:64
	global_load_dwordx4 v[184:187], v[242:243], off offset:512
	global_load_dwordx4 v[188:191], v[242:243], off offset:576
	global_load_dwordx4 v[192:195], v[244:245], off
	global_load_dwordx4 v[208:211], v[244:245], off offset:64
	global_load_dwordx4 v[212:215], v[244:245], off offset:512
	global_load_dwordx4 v[216:219], v[244:245], off offset:576
	global_load_dwordx4 v[220:223], v[246:247], off
	global_load_dwordx4 v[138:141], v[246:247], off offset:64
	global_load_dwordx4 v[134:137], v[246:247], off offset:512
	global_load_dwordx4 v[130:133], v[246:247], off offset:576
	global_store_dwordx4 v[154:155], v[126:129], off
	global_store_dwordx4 v[154:155], v[122:125], off offset:64
	global_store_dwordx4 v[154:155], v[114:117], off offset:512
	global_store_dwordx4 v[154:155], v[110:113], off offset:576
	global_store_dwordx4 v[196:197], v[118:121], off
	global_store_dwordx4 v[196:197], v[106:109], off offset:64
	global_store_dwordx4 v[196:197], v[98:101], off offset:512
	global_store_dwordx4 v[196:197], v[94:97], off offset:576
	global_store_dwordx4 v[224:225], v[102:105], off
	global_store_dwordx4 v[224:225], v[90:93], off offset:64
	global_store_dwordx4 v[224:225], v[82:85], off offset:512
	global_store_dwordx4 v[224:225], v[78:81], off offset:576
	global_store_dwordx4 v[226:227], v[86:89], off
	global_store_dwordx4 v[226:227], v[74:77], off offset:64
	global_store_dwordx4 v[226:227], v[70:73], off offset:512
	global_store_dwordx4 v[226:227], v[66:69], off offset:576
	s_waitcnt vmcnt(0)
	v_pk_add_f32 v[62:63], v[62:63], v[160:161]
	v_pk_add_f32 v[64:65], v[64:65], v[162:163]
	v_pk_add_f32 v[58:59], v[58:59], v[164:165]
	v_pk_add_f32 v[60:61], v[60:61], v[166:167]
	v_pk_add_f32 v[42:43], v[42:43], v[168:169]
	v_pk_add_f32 v[44:45], v[44:45], v[170:171]
	v_pk_add_f32 v[34:35], v[34:35], v[172:173]
	v_pk_add_f32 v[36:37], v[36:37], v[174:175]
	v_pk_add_f32 v[54:55], v[54:55], v[176:177]
	v_pk_add_f32 v[56:57], v[56:57], v[178:179]
	v_pk_add_f32 v[50:51], v[50:51], v[180:181]
	v_pk_add_f32 v[52:53], v[52:53], v[182:183]
	v_pk_add_f32 v[26:27], v[26:27], v[184:185]
	v_pk_add_f32 v[28:29], v[28:29], v[186:187]
	v_pk_add_f32 v[22:23], v[22:23], v[188:189]
	v_pk_add_f32 v[24:25], v[24:25], v[190:191]
	v_pk_add_f32 v[46:47], v[46:47], v[192:193]
	v_pk_add_f32 v[48:49], v[48:49], v[194:195]
	v_pk_add_f32 v[38:39], v[38:39], v[208:209]
	v_pk_add_f32 v[40:41], v[40:41], v[210:211]
	v_pk_add_f32 v[12:13], v[12:13], v[212:213]
	v_pk_add_f32 v[14:15], v[14:15], v[214:215]
	v_pk_add_f32 v[8:9], v[8:9], v[216:217]
	v_pk_add_f32 v[10:11], v[10:11], v[218:219]
	v_pk_add_f32 v[30:31], v[30:31], v[220:221]
	v_pk_add_f32 v[32:33], v[32:33], v[222:223]
	v_pk_add_f32 v[18:19], v[18:19], v[138:139]
	v_pk_add_f32 v[20:21], v[20:21], v[140:141]
	v_pk_add_f32 v[4:5], v[4:5], v[134:135]
	v_pk_add_f32 v[6:7], v[6:7], v[136:137]
	v_pk_add_f32 v[0:1], v[0:1], v[130:131]
	v_pk_add_f32 v[2:3], v[2:3], v[132:133]
	global_store_dwordx4 v[240:241], v[62:65], off
	global_store_dwordx4 v[240:241], v[58:61], off offset:64
	global_store_dwordx4 v[240:241], v[42:45], off offset:512
	global_store_dwordx4 v[240:241], v[34:37], off offset:576
	global_store_dwordx4 v[242:243], v[54:57], off
	global_store_dwordx4 v[242:243], v[50:53], off offset:64
	global_store_dwordx4 v[242:243], v[26:29], off offset:512
	global_store_dwordx4 v[242:243], v[22:25], off offset:576
	global_store_dwordx4 v[244:245], v[46:49], off
	global_store_dwordx4 v[244:245], v[38:41], off offset:64
	global_store_dwordx4 v[244:245], v[12:15], off offset:512
	global_store_dwordx4 v[244:245], v[8:11], off offset:576
	global_store_dwordx4 v[246:247], v[30:33], off
	global_store_dwordx4 v[246:247], v[18:21], off offset:64
	global_store_dwordx4 v[246:247], v[4:7], off offset:512
	global_store_dwordx4 v[246:247], v[0:3], off offset:576
	v_readlane_b32 s82, v255, 5
	s_and_b64 vcc, exec, s[38:39]
	s_mov_b32 s2, s4
	s_mov_b32 s18, s8
	s_mov_b64 s[40:41], s[16:17]
	s_mov_b64 s[22:23], s[14:15]
	v_readlane_b32 s83, v255, 6
	s_cbranch_vccz .LBB0_167
	s_waitcnt vmcnt(0)
	s_cmpk_gt_u32 s35, 0xff
	s_cbranch_scc1 .LBB0_178
	s_barrier
